# s30 + same alignment-barrier move in G1a (leading half's epilogue overlaps the trailing half's last MMA)
# baseline (speedup 1.0000x reference)
; __device__ __forceinline__ unsigned cvt_pk_bf16(float lo, float hi) { const f32x2_t_ v = {lo, hi}; return __builtin_bit_cast(unsigned, __builtin_convertvector(v, bf16x2_t_)); }
; __device__ __forceinline__ float sigmoidf_(float x) { return __builtin_amdgcn_rcpf(1.0f + __expf(-x)); }
; #define PG8_BAR __builtin_amdgcn_s_barrier()
;     __device__ __forceinline__ void operator()(const f32x4 (&acc)[2][2][4][2], const Unit& u, int wr, int wc, int fr, int fq) const {
;         const int row0 = u.pm * BM + wr * 64 + fr, col0 = u.pn * BM + wc * 32 + 8 * fq;
; #pragma unroll
;         for (int ai = 0; ai < 2; ++ai)
; #pragma unroll
;             for (int m = 0; m < 4; ++m) { bf16_t* rowp = O + (size_t)(row0 + ai * HALF + m * 16) * ldc + col0;
; #pragma unroll
;                 for (int bj = 0; bj < 2; ++bj) { f32x4 v0 = acc[ai][bj][m][0], v1 = acc[ai][bj][m][1];
;                     if (u.pn >= sig_from) {
; #pragma unroll
;                         for (int e = 0; e < 4; ++e) { v0[e] = sigmoidf_(v0[e]); v1[e] = sigmoidf_(v1[e]); } }
;                     u32x4 w; w.x = cvt_pk_bf16(v0[0], v0[1]); w.y = cvt_pk_bf16(v0[2], v0[3]); w.z = cvt_pk_bf16(v1[0], v1[1]); w.w = cvt_pk_bf16(v1[2], v1[3]);
;                     *(u32x4*)(rowp + bj * HALF) = w; } }
;     }
; template <class Epi, class Sched, bool ALIGN_EPI = false, bool SP2 = false, bool I8 = false>
; __device__ __forceinline__ void gemm_phase(PG8_LAS unsigned char* lds, const Gemm g, const Sched& S, const Epi& E, const int tid) {
;     ...
;         if constexpr (ALIGN_EPI) { if (wr == 0) PG8_BAR; }
;         if constexpr (!Epi::AFTER_DRAIN) { E(acc, cur, wr, wc, fr, fq); S.done(cur); }
;         if (!has_next) break;
; #pragma unroll
;         for (int a = 0; a < 2; ++a)
; #pragma unroll
;             for (int b = 0; b < 2; ++b)
; #pragma unroll
;                 for (int m = 0; m < 4; ++m)
; #pragma unroll
;                     for (int n = 0; n < 2; ++n) acc[a][b][m][n] = AccT<I8>::zero();
;         cur = nxt; cA = nA; cB = nB; ++ui;
;         if constexpr (ALIGN_EPI) { if (wr == 1) PG8_BAR; }
.LBB0_273:
	v_lshl_or_b32 v144, s10, 8, v142
	v_lshl_add_u32 v150, s12, 8, v140
	v_ashrrev_i32_e32 v145, 31, v144
	v_mov_b64_e32 v[146:147], s[14:15]
	v_cvt_pk_bf16_f32 v68, v68, v69
	v_cvt_pk_bf16_f32 v69, v70, v71
	v_cvt_pk_bf16_f32 v70, v64, v65
	v_add_u32_e32 v64, 0x80, v150
	v_mad_i64_i32 v[148:149], s[10:11], v150, s64, v[146:147]
	v_lshlrev_b64 v[144:145], 1, v[144:145]
	v_cvt_pk_bf16_f32 v110, v110, v111
	v_cvt_pk_bf16_f32 v111, v112, v113
	v_cvt_pk_bf16_f32 v112, v106, v107
	v_or_b32_e32 v106, 16, v150
	v_mad_i64_i32 v[64:65], s[10:11], v64, s64, v[146:147]
	v_cvt_pk_bf16_f32 v44, v44, v45
	v_cvt_pk_bf16_f32 v45, v46, v47
	v_cvt_pk_bf16_f32 v46, v40, v41
	v_add_u32_e32 v40, 0x90, v150
	v_lshl_add_u64 v[148:149], v[148:149], 0, v[144:145]
	v_cvt_pk_bf16_f32 v113, v108, v109
	v_mad_i64_i32 v[106:107], s[10:11], v106, s64, v[146:147]
	v_cvt_pk_bf16_f32 v92, v92, v93
	v_cvt_pk_bf16_f32 v93, v94, v95
	v_cvt_pk_bf16_f32 v94, v88, v89
	v_or_b32_e32 v88, 32, v150
	v_lshl_add_u64 v[64:65], v[64:65], 0, v[144:145]
	v_cvt_pk_bf16_f32 v47, v42, v43
	v_mad_i64_i32 v[40:41], s[10:11], v40, s64, v[146:147]
	v_cvt_pk_bf16_f32 v28, v28, v29
	v_cvt_pk_bf16_f32 v29, v30, v31
	v_cvt_pk_bf16_f32 v30, v24, v25
	v_add_u32_e32 v24, 0xa0, v150
	global_store_dwordx4 v[148:149], v[110:113], off offset:256
	v_cvt_pk_bf16_f32 v95, v90, v91
	v_mad_i64_i32 v[88:89], s[10:11], v88, s64, v[146:147]
	v_lshl_add_u64 v[110:111], v[106:107], 0, v[144:145]
	v_cvt_pk_bf16_f32 v76, v76, v77
	v_cvt_pk_bf16_f32 v77, v78, v79
	v_cvt_pk_bf16_f32 v78, v72, v73
	v_or_b32_e32 v72, 48, v150
	global_store_dwordx4 v[64:65], v[44:47], off offset:256
	v_cvt_pk_bf16_f32 v31, v26, v27
	v_mad_i64_i32 v[24:25], s[10:11], v24, s64, v[146:147]
	v_lshl_add_u64 v[44:45], v[40:41], 0, v[144:145]
	v_cvt_pk_bf16_f32 v12, v12, v13
	v_cvt_pk_bf16_f32 v13, v14, v15
	v_cvt_pk_bf16_f32 v14, v8, v9
	v_add_u32_e32 v8, 0xb0, v150
	global_store_dwordx4 v[110:111], v[92:95], off offset:256
	v_cvt_pk_bf16_f32 v79, v74, v75
	v_mad_i64_i32 v[72:73], s[10:11], v72, s64, v[146:147]
	v_lshl_add_u64 v[92:93], v[88:89], 0, v[144:145]
	global_store_dwordx4 v[44:45], v[28:31], off offset:256
	v_cvt_pk_bf16_f32 v15, v10, v11
	v_mad_i64_i32 v[8:9], s[10:11], v8, s64, v[146:147]
	v_lshl_add_u64 v[28:29], v[24:25], 0, v[144:145]
	v_cvt_pk_bf16_f32 v126, v126, v127
	v_cvt_pk_bf16_f32 v127, v128, v129
	v_cvt_pk_bf16_f32 v128, v122, v123
	v_cvt_pk_bf16_f32 v129, v124, v125
	v_cvt_pk_bf16_f32 v106, v118, v119
	v_cvt_pk_bf16_f32 v107, v120, v121
	v_cvt_pk_bf16_f32 v108, v114, v115
	v_cvt_pk_bf16_f32 v109, v116, v117
	v_cvt_pk_bf16_f32 v88, v102, v103
	v_cvt_pk_bf16_f32 v89, v104, v105
	v_cvt_pk_bf16_f32 v90, v98, v99
	v_cvt_pk_bf16_f32 v91, v100, v101
	global_store_dwordx4 v[92:93], v[76:79], off offset:256
	v_cvt_pk_bf16_f32 v74, v80, v81
	v_cvt_pk_bf16_f32 v75, v82, v83
	v_lshl_add_u64 v[76:77], v[72:73], 0, v[144:145]
	v_cvt_pk_bf16_f32 v72, v84, v85
	v_cvt_pk_bf16_f32 v73, v86, v87
	v_cvt_pk_bf16_f32 v71, v66, v67
	v_cvt_pk_bf16_f32 v60, v60, v61
	v_cvt_pk_bf16_f32 v61, v62, v63
	v_cvt_pk_bf16_f32 v62, v56, v57
	v_cvt_pk_bf16_f32 v63, v58, v59
	v_cvt_pk_bf16_f32 v40, v52, v53
	v_cvt_pk_bf16_f32 v41, v54, v55
	v_cvt_pk_bf16_f32 v42, v48, v49
	v_cvt_pk_bf16_f32 v43, v50, v51
	v_cvt_pk_bf16_f32 v24, v36, v37
	v_cvt_pk_bf16_f32 v25, v38, v39
	v_cvt_pk_bf16_f32 v26, v32, v33
	v_cvt_pk_bf16_f32 v27, v34, v35
	global_store_dwordx4 v[28:29], v[12:15], off offset:256
	v_cvt_pk_bf16_f32 v10, v16, v17
	v_cvt_pk_bf16_f32 v11, v18, v19
	v_lshl_add_u64 v[12:13], v[8:9], 0, v[144:145]
	v_cvt_pk_bf16_f32 v8, v20, v21
	v_cvt_pk_bf16_f32 v9, v22, v23
	v_cvt_pk_bf16_f32 v4, v4, v5
	v_cvt_pk_bf16_f32 v5, v6, v7
	v_cvt_pk_bf16_f32 v6, v0, v1
	v_cvt_pk_bf16_f32 v7, v2, v3
	s_and_b64 vcc, exec, s[22:23]
	s_cbranch_vccz .Lepi_nb_a
	s_barrier
.Lepi_nb_a:
	s_andn2_b64 vcc, exec, s[34:35]
	s_mov_b64 s[10:11], -1
	s_mov_b64 s[86:87], 0x5000
	s_mov_b64 s[90:91], 0x1800
	global_store_dwordx4 v[148:149], v[126:129], off
	global_store_dwordx4 v[110:111], v[106:109], off
	global_store_dwordx4 v[92:93], v[88:91], off
	global_store_dwordx4 v[76:77], v[72:75], off
	global_store_dwordx4 v[76:77], v[68:71], off offset:256
	global_store_dwordx4 v[64:65], v[60:63], off
	global_store_dwordx4 v[44:45], v[40:43], off
	global_store_dwordx4 v[28:29], v[24:27], off
	global_store_dwordx4 v[12:13], v[8:11], off
	global_store_dwordx4 v[12:13], v[4:7], off offset:256
	s_cbranch_vccnz .LBB0_242
	s_andn2_b64 vcc, exec, s[8:9]
	s_cbranch_vccnz .LBB0_241
	s_barrier
	s_branch .LBB0_241
